# adds: per-workgroup L1 invalidate issued with the barrier arrival instead of after the release
# speedup vs baseline: 1.0264x; 1.0047x over previous
.LBB0_326:
	s_mov_b64 s[6:7], exec
	v_mbcnt_lo_u32_b32 v0, s6, 0
	v_mbcnt_hi_u32_b32 v0, s7, v0
	v_cmp_eq_u32_e32 vcc, 0, v0
	s_and_saveexec_b64 s[4:5], vcc
	s_cbranch_execz .LBB0_328
	s_bcnt1_i32_b64 s6, s[6:7]
	v_mov_b32_e32 v4, s6
	v_readlane_b32 s6, v254, 14
	v_readlane_b32 s7, v254, 15
	s_nop 4
	global_atomic_add v4, v1, v4, s[6:7] sc0
	buffer_inv sc1

.LBB0_341:
	s_or_b64 exec, exec, s[6:7]
	s_waitcnt vmcnt(0)
	s_waitcnt vmcnt(0)

.LBB0_359:
	s_or_b64 exec, exec, s[4:5]
	s_mov_b64 s[4:5], exec
	v_mbcnt_lo_u32_b32 v0, s4, 0
	v_mbcnt_hi_u32_b32 v0, s5, v0
	v_cmp_eq_u32_e32 vcc, 0, v0
	s_waitcnt vmcnt(0)
	s_and_saveexec_b64 s[6:7], vcc
	s_cbranch_execz .LBB0_361
	s_bcnt1_i32_b64 s4, s[4:5]
	v_mov_b32_e32 v0, s4
	v_readlane_b32 s4, v254, 16
	v_readlane_b32 s5, v254, 17
	s_nop 4
	global_atomic_add v1, v0, s[4:5]

.LBB0_971:
	s_or_b64 exec, exec, s[4:5]
	s_mov_b64 s[4:5], exec
	v_mbcnt_lo_u32_b32 v0, s4, 0
	v_mbcnt_hi_u32_b32 v0, s5, v0
	v_cmp_eq_u32_e32 vcc, 0, v0
	s_waitcnt vmcnt(0)
	s_and_saveexec_b64 s[6:7], vcc
	s_cbranch_execz .LBB0_91
	s_bcnt1_i32_b64 s4, s[4:5]
	v_mov_b32_e32 v0, s4
	v_readlane_b32 s4, v254, 16
	v_readlane_b32 s5, v254, 17
	s_nop 4
	global_atomic_add v1, v0, s[4:5]
	s_branch .LBB0_91
